# in-proj GELU epilogue: argument computed as v*fma(v*v, k*c, k) with v_fmaak (3 ops instead of 4 per element, 128 sites), same f32 math
# speedup vs baseline: 1.0056x; 1.0056x over previous
.LBB0_207:
	s_add_u32 s50, s54, 0xc000000
	s_addc_u32 s51, s55, 0
	s_lshl_b32 s5, s5, 5
	s_mov_b64 s[12:13], 0x80
	s_and_b32 s5, s5, 0x60
	s_add_i32 m0, s31, 0x18000
	v_lshl_add_u64 v[6:7], v[6:7], 0, s[12:13]
	s_lshl_b32 s7, s4, 13
	s_lshl_b32 s15, s5, 7
	s_waitcnt vmcnt(2)
	s_barrier
	global_load_lds_dwordx4 v[6:7], off
	v_lshl_add_u64 v[2:3], v[2:3], 0, s[12:13]
	s_add_i32 m0, s31, 0x1a000
	s_add_i32 s60, s31, 0x8000
	s_add_i32 s61, s31, 0xa000
	global_load_lds_dwordx4 v[2:3], off
	v_lshl_add_u64 v[0:1], v[0:1], 0, s[12:13]
	s_mov_b32 m0, s60
	s_add_u32 s16, s36, 0x40080
	global_load_lds_dwordx4 v[0:1], off
	v_lshl_add_u64 v[0:1], v[4:5], 0, s[12:13]
	s_mov_b32 m0, s61
	s_addc_u32 s17, s37, 0
	global_load_lds_dwordx4 v[0:1], off
	s_add_i32 m0, s31, 0x1c000
	v_lshl_add_u64 v[0:1], s[16:17], 0, v[130:131]
	global_load_lds_dwordx4 v[0:1], off
	v_lshl_add_u64 v[0:1], s[16:17], 0, v[134:135]
	s_add_i32 m0, s31, 0x1e000
	s_cmpk_lt_u32 s14, 0x100
	global_load_lds_dwordx4 v[0:1], off
	v_lshrrev_b32_e32 v1, 1, v8
	v_and_b32_e32 v1, 24, v1
	v_and_b32_e32 v0, 15, v8
	v_lshlrev_b32_e32 v2, 1, v1
	v_lshl_or_b32 v152, s4, 6, v0
	v_lshl_or_b32 v0, v0, 6, v2
	v_lshlrev_b32_e32 v2, 2, v8
	v_and_b32_e32 v2, 32, v2
	v_bitop3_b32 v3, v0, s7, v2 bitop3:0xde
	v_bitop3_b32 v153, v0, s15, v2 bitop3:0xde
	v_lshlrev_b32_e32 v0, 14, v9
	v_and_b32_e32 v0, 0xffff8000, v0
	v_or_b32_e32 v154, s5, v1
	v_lshl_add_u32 v0, v10, 11, v0
	v_and_b32_e32 v1, 1, v9
	v_lshl_or_b32 v0, v1, 6, v0
	v_lshl_add_u32 v138, v11, 1, v0
	v_lshlrev_b32_e32 v0, 14, v12
	v_and_b32_e32 v0, 0xffff8000, v0
	s_waitcnt vmcnt(6)
	v_lshl_add_u32 v0, v13, 11, v0
	v_and_b32_e32 v1, 1, v12
	s_cselect_b64 s[14:15], -1, 0
	v_lshl_or_b32 v0, v1, 6, v0
	s_add_i32 s65, 0, 0x10000
	s_add_i32 s67, 0, 0x14000
	s_ashr_i32 s62, s52, 31
	s_mov_b32 s63, s52
	s_ashr_i32 s64, s33, 31
	v_mov_b32_e32 v139, v137
	v_lshl_add_u32 v140, v14, 1, v0
	v_mov_b32_e32 v141, v137
	v_mov_b64_e32 v[142:143], 0x400
	v_mov_b64_e32 v[144:145], 0x3ff
	v_add_u32_e32 v155, s65, v153
	v_add_u32_e32 v156, s67, v153
	v_add_u32_e32 v157, 0, v3
	s_mov_b64 s[16:17], 0x48000
	s_mov_b64 s[18:19], 0x50000
	s_mov_b64 s[20:21], 0x58000
	s_barrier
	v_mov_b32_e32 v254, 0xbdd2d3e7
	s_branch .LBB0_210

.LBB0_220:
	s_cmp_lt_i32 s30, 4
	s_cselect_b64 s[34:35], -1, 0
	s_cmp_gt_i32 s30, 3
	s_cbranch_scc1 .LBB0_222
	v_mul_f32_e32 v146, v120, v120
	v_fmaak_f32 v146, v254, v146, 0xc0135761
	v_mul_f32_e32 v136, v124, v124
	v_mul_f32_e32 v146, v120, v146
	v_fmaak_f32 v136, v254, v136, 0xc0135761
	v_mul_f32_e32 v136, v124, v136
	v_exp_f32_e32 v147, v146
	v_mul_f32_e32 v146, v125, v125
	v_fmaak_f32 v146, v254, v146, 0xc0135761
	v_exp_f32_e32 v136, v136
	v_mul_f32_e32 v146, v125, v146
	v_exp_f32_e32 v149, v146
	v_add_f32_e32 v136, 1.0, v136
	v_rcp_f32_e32 v146, v136
	v_add_f32_e32 v136, 1.0, v147
	v_rcp_f32_e32 v148, v136
	v_add_f32_e32 v136, 1.0, v149
	v_mul_f32_e32 v149, v126, v126
	v_fmaak_f32 v149, v254, v149, 0xc0135761
	v_mul_f32_e32 v150, v122, v122
	v_mul_f32_e32 v149, v126, v149
	v_fmaak_f32 v150, v254, v150, 0xc0135761
	v_mul_f32_e32 v150, v122, v150
	v_exp_f32_e32 v149, v149
	v_exp_f32_e32 v151, v150
	v_rcp_f32_e32 v147, v136
	v_add_f32_e32 v149, 1.0, v149
	v_rcp_f32_e32 v150, v149
	v_add_f32_e32 v149, 1.0, v151
	v_mul_f32_e32 v151, v127, v127
	v_mul_f32_e32 v136, v121, v121
	v_fmaak_f32 v151, v254, v151, 0xc0135761
	v_mul_f32_e32 v158, v123, v123
	v_fmaak_f32 v136, v254, v136, 0xc0135761
	v_mul_f32_e32 v151, v127, v151
	v_fmaak_f32 v158, v254, v158, 0xc0135761
	v_mul_f32_e32 v136, v121, v136
	v_mul_f32_e32 v158, v123, v158
	v_exp_f32_e32 v151, v151
	v_exp_f32_e32 v136, v136
	v_exp_f32_e32 v159, v158
	v_rcp_f32_e32 v158, v149
	v_add_f32_e32 v149, 1.0, v151
	v_add_f32_e32 v136, 1.0, v136
	v_rcp_f32_e32 v151, v149
	v_add_f32_e32 v149, 1.0, v159
	v_rcp_f32_e32 v159, v149
	v_rcp_f32_e32 v149, v136
	v_pk_mul_f32 v[126:127], v[126:127], v[150:151]
	v_pk_mul_f32 v[124:125], v[124:125], v[146:147]
	v_pk_mul_f32 v[122:123], v[122:123], v[158:159]
	v_pk_mul_f32 v[120:121], v[120:121], v[148:149]
.LBB0_222:
	s_and_b64 s[36:37], s[34:35], exec
	s_cselect_b32 s37, s57, s51
	s_cselect_b32 s36, s56, s50
	v_lshl_add_u32 v146, s6, 8, v152
	s_lshl_b32 s6, s30, 8
	s_and_b32 s6, s6, 0x300
	v_or_b32_e32 v136, s6, v154
	v_lshlrev_b32_e32 v136, 1, v136
	v_ashrrev_i32_e32 v147, 31, v146
	v_lshl_add_u64 v[148:149], s[36:37], 0, v[136:137]
	v_lshlrev_b64 v[150:151], 11, v[146:147]
	v_cvt_pk_bf16_f32 v124, v124, v125
	v_cvt_pk_bf16_f32 v125, v126, v127
	v_cvt_pk_bf16_f32 v126, v120, v121
	v_cndmask_b32_e64 v120, 0, 1, s[34:35]
	v_lshl_add_u64 v[150:151], v[148:149], 0, v[150:151]
	v_cmp_ne_u32_e64 s[6:7], 1, v120
	s_andn2_b64 vcc, exec, s[34:35]
	v_cvt_pk_bf16_f32 v127, v122, v123
	global_store_dwordx4 v[150:151], v[124:127], off
	s_cbranch_vccnz .LBB0_224
	v_mul_f32_e32 v121, v112, v112
	v_fmaak_f32 v121, v254, v121, 0xc0135761
	v_mul_f32_e32 v122, v117, v117
	v_mul_f32_e32 v121, v112, v121
	v_fmaak_f32 v122, v254, v122, 0xc0135761
	v_mul_f32_e32 v122, v117, v122
	v_exp_f32_e32 v121, v121
	v_exp_f32_e32 v123, v122
	v_mul_f32_e32 v126, v119, v119
	v_fmaak_f32 v126, v254, v126, 0xc0135761
	v_mul_f32_e32 v126, v119, v126
	v_add_f32_e32 v121, 1.0, v121
	v_mul_f32_e32 v125, v114, v114
	v_mul_f32_e32 v120, v116, v116
	v_rcp_f32_e32 v122, v121
	v_add_f32_e32 v121, 1.0, v123
	v_mul_f32_e32 v123, v113, v113
	v_mul_f32_e32 v124, v118, v118
	v_fmaak_f32 v125, v254, v125, 0xc0135761
	v_exp_f32_e32 v127, v126
	v_mul_f32_e32 v126, v115, v115
	v_fmaak_f32 v120, v254, v120, 0xc0135761
	v_fmaak_f32 v123, v254, v123, 0xc0135761
	v_fmaak_f32 v124, v254, v124, 0xc0135761
	v_mul_f32_e32 v125, v114, v125
	v_fmaak_f32 v126, v254, v126, 0xc0135761
	v_mul_f32_e32 v120, v116, v120
	v_mul_f32_e32 v123, v113, v123
	v_mul_f32_e32 v124, v118, v124
	v_mul_f32_e32 v126, v115, v126
	v_exp_f32_e32 v125, v125
	v_exp_f32_e32 v120, v120
	v_exp_f32_e32 v123, v123
	v_exp_f32_e32 v124, v124
	v_exp_f32_e32 v136, v126
	v_add_f32_e32 v125, 1.0, v125
	v_add_f32_e32 v120, 1.0, v120
	v_add_f32_e32 v123, 1.0, v123
	v_add_f32_e32 v124, 1.0, v124
	v_rcp_f32_e32 v126, v125
	v_add_f32_e32 v125, 1.0, v127
	v_add_f32_e32 v127, 1.0, v136
	v_rcp_f32_e32 v120, v120
	v_rcp_f32_e32 v121, v121
	v_rcp_f32_e32 v124, v124
	v_rcp_f32_e32 v125, v125
	v_rcp_f32_e32 v127, v127
	v_rcp_f32_e32 v123, v123
	v_pk_mul_f32 v[116:117], v[116:117], v[120:121]
	v_pk_mul_f32 v[118:119], v[118:119], v[124:125]
	v_pk_mul_f32 v[114:115], v[114:115], v[126:127]
	v_pk_mul_f32 v[112:113], v[112:113], v[122:123]
.LBB0_224:
	s_and_b64 vcc, exec, s[6:7]
	v_cvt_pk_bf16_f32 v116, v116, v117
	v_cvt_pk_bf16_f32 v117, v118, v119
	v_cvt_pk_bf16_f32 v118, v112, v113
	v_cvt_pk_bf16_f32 v119, v114, v115
	global_store_dwordx4 v[150:151], v[116:119], off offset:256
	s_cbranch_vccnz .LBB0_226
	v_mul_f32_e32 v113, v104, v104
	v_fmaak_f32 v113, v254, v113, 0xc0135761
	v_mul_f32_e32 v114, v109, v109
	v_mul_f32_e32 v113, v104, v113
	v_fmaak_f32 v114, v254, v114, 0xc0135761
	v_mul_f32_e32 v114, v109, v114
	v_exp_f32_e32 v113, v113
	v_exp_f32_e32 v115, v114
	v_mul_f32_e32 v118, v111, v111
	v_fmaak_f32 v118, v254, v118, 0xc0135761
	v_mul_f32_e32 v118, v111, v118
	v_add_f32_e32 v113, 1.0, v113
	v_mul_f32_e32 v117, v106, v106
	v_mul_f32_e32 v112, v108, v108
	v_rcp_f32_e32 v114, v113
	v_add_f32_e32 v113, 1.0, v115
	v_mul_f32_e32 v115, v105, v105
	v_mul_f32_e32 v116, v110, v110
	v_fmaak_f32 v117, v254, v117, 0xc0135761
	v_exp_f32_e32 v119, v118
	v_mul_f32_e32 v118, v107, v107
	v_fmaak_f32 v112, v254, v112, 0xc0135761
	v_fmaak_f32 v115, v254, v115, 0xc0135761
	v_fmaak_f32 v116, v254, v116, 0xc0135761
	v_mul_f32_e32 v117, v106, v117
	v_fmaak_f32 v118, v254, v118, 0xc0135761
	v_mul_f32_e32 v112, v108, v112
	v_mul_f32_e32 v115, v105, v115
	v_mul_f32_e32 v116, v110, v116
	v_mul_f32_e32 v118, v107, v118
	v_exp_f32_e32 v117, v117
	v_exp_f32_e32 v112, v112
	v_exp_f32_e32 v115, v115
	v_exp_f32_e32 v116, v116
	v_exp_f32_e32 v120, v118
	v_add_f32_e32 v117, 1.0, v117
	v_add_f32_e32 v112, 1.0, v112
	v_add_f32_e32 v115, 1.0, v115
	v_add_f32_e32 v116, 1.0, v116
	v_rcp_f32_e32 v118, v117
	v_add_f32_e32 v117, 1.0, v119
	v_add_f32_e32 v119, 1.0, v120
	v_rcp_f32_e32 v112, v112
	v_rcp_f32_e32 v113, v113
	v_rcp_f32_e32 v116, v116
	v_rcp_f32_e32 v117, v117
	v_rcp_f32_e32 v119, v119
	v_rcp_f32_e32 v115, v115
	v_pk_mul_f32 v[108:109], v[108:109], v[112:113]
	v_pk_mul_f32 v[110:111], v[110:111], v[116:117]
	v_pk_mul_f32 v[106:107], v[106:107], v[118:119]
	v_pk_mul_f32 v[104:105], v[104:105], v[114:115]
.LBB0_226:
	v_or_b32_e32 v112, 16, v146
	v_ashrrev_i32_e32 v113, 31, v112
	v_lshlrev_b64 v[112:113], 11, v[112:113]
	v_lshl_add_u64 v[112:113], v[148:149], 0, v[112:113]
	s_and_b64 vcc, exec, s[6:7]
	v_cvt_pk_bf16_f32 v108, v108, v109
	v_cvt_pk_bf16_f32 v109, v110, v111
	v_cvt_pk_bf16_f32 v110, v104, v105
	v_cvt_pk_bf16_f32 v111, v106, v107
	global_store_dwordx4 v[112:113], v[108:111], off
	s_cbranch_vccnz .LBB0_228
	v_mul_f32_e32 v105, v96, v96
	v_fmaak_f32 v105, v254, v105, 0xc0135761
	v_mul_f32_e32 v106, v101, v101
	v_mul_f32_e32 v105, v96, v105
	v_fmaak_f32 v106, v254, v106, 0xc0135761
	v_mul_f32_e32 v106, v101, v106
	v_exp_f32_e32 v105, v105
	v_exp_f32_e32 v107, v106
	v_mul_f32_e32 v110, v103, v103
	v_fmaak_f32 v110, v254, v110, 0xc0135761
	v_mul_f32_e32 v110, v103, v110
	v_add_f32_e32 v105, 1.0, v105
	v_mul_f32_e32 v109, v98, v98
	v_mul_f32_e32 v104, v100, v100
	v_rcp_f32_e32 v106, v105
	v_add_f32_e32 v105, 1.0, v107
	v_mul_f32_e32 v107, v97, v97
	v_mul_f32_e32 v108, v102, v102
	v_fmaak_f32 v109, v254, v109, 0xc0135761
	v_exp_f32_e32 v111, v110
	v_mul_f32_e32 v110, v99, v99
	v_fmaak_f32 v104, v254, v104, 0xc0135761
	v_fmaak_f32 v107, v254, v107, 0xc0135761
	v_fmaak_f32 v108, v254, v108, 0xc0135761
	v_mul_f32_e32 v109, v98, v109
	v_fmaak_f32 v110, v254, v110, 0xc0135761
	v_mul_f32_e32 v104, v100, v104
	v_mul_f32_e32 v107, v97, v107
	v_mul_f32_e32 v108, v102, v108
	v_mul_f32_e32 v110, v99, v110
	v_exp_f32_e32 v109, v109
	v_exp_f32_e32 v104, v104
	v_exp_f32_e32 v107, v107
	v_exp_f32_e32 v108, v108
	v_exp_f32_e32 v114, v110
	v_add_f32_e32 v109, 1.0, v109
	v_add_f32_e32 v104, 1.0, v104
	v_add_f32_e32 v107, 1.0, v107
	v_add_f32_e32 v108, 1.0, v108
	v_rcp_f32_e32 v110, v109
	v_add_f32_e32 v109, 1.0, v111
	v_add_f32_e32 v111, 1.0, v114
	v_rcp_f32_e32 v104, v104
	v_rcp_f32_e32 v105, v105
	v_rcp_f32_e32 v108, v108
	v_rcp_f32_e32 v109, v109
	v_rcp_f32_e32 v111, v111
	v_rcp_f32_e32 v107, v107
	v_pk_mul_f32 v[100:101], v[100:101], v[104:105]
	v_pk_mul_f32 v[102:103], v[102:103], v[108:109]
	v_pk_mul_f32 v[98:99], v[98:99], v[110:111]
	v_pk_mul_f32 v[96:97], v[96:97], v[106:107]
.LBB0_228:
	s_and_b64 vcc, exec, s[6:7]
	v_cvt_pk_bf16_f32 v100, v100, v101
	v_cvt_pk_bf16_f32 v101, v102, v103
	v_cvt_pk_bf16_f32 v102, v96, v97
	v_cvt_pk_bf16_f32 v103, v98, v99
	global_store_dwordx4 v[112:113], v[100:103], off offset:256
	s_cbranch_vccnz .LBB0_230
	v_mul_f32_e32 v97, v88, v88
	v_fmaak_f32 v97, v254, v97, 0xc0135761
	v_mul_f32_e32 v98, v93, v93
	v_mul_f32_e32 v97, v88, v97
	v_fmaak_f32 v98, v254, v98, 0xc0135761
	v_mul_f32_e32 v98, v93, v98
	v_exp_f32_e32 v97, v97
	v_exp_f32_e32 v99, v98
	v_mul_f32_e32 v102, v95, v95
	v_fmaak_f32 v102, v254, v102, 0xc0135761
	v_mul_f32_e32 v102, v95, v102
	v_add_f32_e32 v97, 1.0, v97
	v_mul_f32_e32 v101, v90, v90
	v_mul_f32_e32 v96, v92, v92
	v_rcp_f32_e32 v98, v97
	v_add_f32_e32 v97, 1.0, v99
	v_mul_f32_e32 v99, v89, v89
	v_mul_f32_e32 v100, v94, v94
	v_fmaak_f32 v101, v254, v101, 0xc0135761
	v_exp_f32_e32 v103, v102
	v_mul_f32_e32 v102, v91, v91
	v_fmaak_f32 v96, v254, v96, 0xc0135761
	v_fmaak_f32 v99, v254, v99, 0xc0135761
	v_fmaak_f32 v100, v254, v100, 0xc0135761
	v_mul_f32_e32 v101, v90, v101
	v_fmaak_f32 v102, v254, v102, 0xc0135761
	v_mul_f32_e32 v96, v92, v96
	v_mul_f32_e32 v99, v89, v99
	v_mul_f32_e32 v100, v94, v100
	v_mul_f32_e32 v102, v91, v102
	v_exp_f32_e32 v101, v101
	v_exp_f32_e32 v96, v96
	v_exp_f32_e32 v99, v99
	v_exp_f32_e32 v100, v100
	v_exp_f32_e32 v104, v102
	v_add_f32_e32 v101, 1.0, v101
	v_add_f32_e32 v96, 1.0, v96
	v_add_f32_e32 v99, 1.0, v99
	v_add_f32_e32 v100, 1.0, v100
	v_rcp_f32_e32 v102, v101
	v_add_f32_e32 v101, 1.0, v103
	v_add_f32_e32 v103, 1.0, v104
	v_rcp_f32_e32 v96, v96
	v_rcp_f32_e32 v97, v97
	v_rcp_f32_e32 v100, v100
	v_rcp_f32_e32 v101, v101
	v_rcp_f32_e32 v103, v103
	v_rcp_f32_e32 v99, v99
	v_pk_mul_f32 v[92:93], v[92:93], v[96:97]
	v_pk_mul_f32 v[94:95], v[94:95], v[100:101]
	v_pk_mul_f32 v[90:91], v[90:91], v[102:103]
	v_pk_mul_f32 v[88:89], v[88:89], v[98:99]
.LBB0_230:
	v_or_b32_e32 v96, 32, v146
	v_ashrrev_i32_e32 v97, 31, v96
	v_lshlrev_b64 v[96:97], 11, v[96:97]
	v_lshl_add_u64 v[96:97], v[148:149], 0, v[96:97]
	s_and_b64 vcc, exec, s[6:7]
	v_cvt_pk_bf16_f32 v92, v92, v93
	v_cvt_pk_bf16_f32 v93, v94, v95
	v_cvt_pk_bf16_f32 v94, v88, v89
	v_cvt_pk_bf16_f32 v95, v90, v91
	global_store_dwordx4 v[96:97], v[92:95], off
	s_cbranch_vccnz .LBB0_232
	v_mul_f32_e32 v89, v80, v80
	v_fmaak_f32 v89, v254, v89, 0xc0135761
	v_mul_f32_e32 v90, v85, v85
	v_mul_f32_e32 v89, v80, v89
	v_fmaak_f32 v90, v254, v90, 0xc0135761
	v_mul_f32_e32 v90, v85, v90
	v_exp_f32_e32 v89, v89
	v_exp_f32_e32 v91, v90
	v_mul_f32_e32 v94, v87, v87
	v_fmaak_f32 v94, v254, v94, 0xc0135761
	v_mul_f32_e32 v94, v87, v94
	v_add_f32_e32 v89, 1.0, v89
	v_mul_f32_e32 v93, v82, v82
	v_mul_f32_e32 v88, v84, v84
	v_rcp_f32_e32 v90, v89
	v_add_f32_e32 v89, 1.0, v91
	v_mul_f32_e32 v91, v81, v81
	v_mul_f32_e32 v92, v86, v86
	v_fmaak_f32 v93, v254, v93, 0xc0135761
	v_exp_f32_e32 v95, v94
	v_mul_f32_e32 v94, v83, v83
	v_fmaak_f32 v88, v254, v88, 0xc0135761
	v_fmaak_f32 v91, v254, v91, 0xc0135761
	v_fmaak_f32 v92, v254, v92, 0xc0135761
	v_mul_f32_e32 v93, v82, v93
	v_fmaak_f32 v94, v254, v94, 0xc0135761
	v_mul_f32_e32 v88, v84, v88
	v_mul_f32_e32 v91, v81, v91
	v_mul_f32_e32 v92, v86, v92
	v_mul_f32_e32 v94, v83, v94
	v_exp_f32_e32 v93, v93
	v_exp_f32_e32 v88, v88
	v_exp_f32_e32 v91, v91
	v_exp_f32_e32 v92, v92
	v_exp_f32_e32 v98, v94
	v_add_f32_e32 v93, 1.0, v93
	v_add_f32_e32 v88, 1.0, v88
	v_add_f32_e32 v91, 1.0, v91
	v_add_f32_e32 v92, 1.0, v92
	v_rcp_f32_e32 v94, v93
	v_add_f32_e32 v93, 1.0, v95
	v_add_f32_e32 v95, 1.0, v98
	v_rcp_f32_e32 v88, v88
	v_rcp_f32_e32 v89, v89
	v_rcp_f32_e32 v92, v92
	v_rcp_f32_e32 v93, v93
	v_rcp_f32_e32 v95, v95
	v_rcp_f32_e32 v91, v91
	v_pk_mul_f32 v[84:85], v[84:85], v[88:89]
	v_pk_mul_f32 v[86:87], v[86:87], v[92:93]
	v_pk_mul_f32 v[82:83], v[82:83], v[94:95]
	v_pk_mul_f32 v[80:81], v[80:81], v[90:91]
.LBB0_232:
	s_and_b64 vcc, exec, s[6:7]
	v_cvt_pk_bf16_f32 v84, v84, v85
	v_cvt_pk_bf16_f32 v85, v86, v87
	v_cvt_pk_bf16_f32 v86, v80, v81
	v_cvt_pk_bf16_f32 v87, v82, v83
	global_store_dwordx4 v[96:97], v[84:87], off offset:256
	s_cbranch_vccnz .LBB0_234
	v_mul_f32_e32 v81, v72, v72
	v_fmaak_f32 v81, v254, v81, 0xc0135761
	v_mul_f32_e32 v82, v77, v77
	v_mul_f32_e32 v81, v72, v81
	v_fmaak_f32 v82, v254, v82, 0xc0135761
	v_mul_f32_e32 v82, v77, v82
	v_exp_f32_e32 v81, v81
	v_exp_f32_e32 v83, v82
	v_mul_f32_e32 v86, v79, v79
	v_fmaak_f32 v86, v254, v86, 0xc0135761
	v_mul_f32_e32 v86, v79, v86
	v_add_f32_e32 v81, 1.0, v81
	v_mul_f32_e32 v85, v74, v74
	v_mul_f32_e32 v80, v76, v76
	v_rcp_f32_e32 v82, v81
	v_add_f32_e32 v81, 1.0, v83
	v_mul_f32_e32 v83, v73, v73
	v_mul_f32_e32 v84, v78, v78
	v_fmaak_f32 v85, v254, v85, 0xc0135761
	v_exp_f32_e32 v87, v86
	v_mul_f32_e32 v86, v75, v75
	v_fmaak_f32 v80, v254, v80, 0xc0135761
	v_fmaak_f32 v83, v254, v83, 0xc0135761
	v_fmaak_f32 v84, v254, v84, 0xc0135761
	v_mul_f32_e32 v85, v74, v85
	v_fmaak_f32 v86, v254, v86, 0xc0135761
	v_mul_f32_e32 v80, v76, v80
	v_mul_f32_e32 v83, v73, v83
	v_mul_f32_e32 v84, v78, v84
	v_mul_f32_e32 v86, v75, v86
	v_exp_f32_e32 v85, v85
	v_exp_f32_e32 v80, v80
	v_exp_f32_e32 v83, v83
	v_exp_f32_e32 v84, v84
	v_exp_f32_e32 v88, v86
	v_add_f32_e32 v85, 1.0, v85
	v_add_f32_e32 v80, 1.0, v80
	v_add_f32_e32 v83, 1.0, v83
	v_add_f32_e32 v84, 1.0, v84
	v_rcp_f32_e32 v86, v85
	v_add_f32_e32 v85, 1.0, v87
	v_add_f32_e32 v87, 1.0, v88
	v_rcp_f32_e32 v80, v80
	v_rcp_f32_e32 v81, v81
	v_rcp_f32_e32 v84, v84
	v_rcp_f32_e32 v85, v85
	v_rcp_f32_e32 v87, v87
	v_rcp_f32_e32 v83, v83
	v_pk_mul_f32 v[76:77], v[76:77], v[80:81]
	v_pk_mul_f32 v[78:79], v[78:79], v[84:85]
	v_pk_mul_f32 v[74:75], v[74:75], v[86:87]
	v_pk_mul_f32 v[72:73], v[72:73], v[82:83]
.LBB0_234:
	v_or_b32_e32 v80, 48, v146
	v_ashrrev_i32_e32 v81, 31, v80
	v_lshlrev_b64 v[80:81], 11, v[80:81]
	v_lshl_add_u64 v[80:81], v[148:149], 0, v[80:81]
	s_and_b64 vcc, exec, s[6:7]
	v_cvt_pk_bf16_f32 v76, v76, v77
	v_cvt_pk_bf16_f32 v77, v78, v79
	v_cvt_pk_bf16_f32 v78, v72, v73
	v_cvt_pk_bf16_f32 v79, v74, v75
	global_store_dwordx4 v[80:81], v[76:79], off
	s_cbranch_vccnz .LBB0_236
	v_mul_f32_e32 v73, v64, v64
	v_fmaak_f32 v73, v254, v73, 0xc0135761
	v_mul_f32_e32 v74, v69, v69
	v_mul_f32_e32 v73, v64, v73
	v_fmaak_f32 v74, v254, v74, 0xc0135761
	v_mul_f32_e32 v74, v69, v74
	v_exp_f32_e32 v73, v73
	v_exp_f32_e32 v75, v74
	v_mul_f32_e32 v78, v71, v71
	v_fmaak_f32 v78, v254, v78, 0xc0135761
	v_mul_f32_e32 v78, v71, v78
	v_add_f32_e32 v73, 1.0, v73
	v_mul_f32_e32 v77, v66, v66
	v_mul_f32_e32 v72, v68, v68
	v_rcp_f32_e32 v74, v73
	v_add_f32_e32 v73, 1.0, v75
	v_mul_f32_e32 v75, v65, v65
	v_mul_f32_e32 v76, v70, v70
	v_fmaak_f32 v77, v254, v77, 0xc0135761
	v_exp_f32_e32 v79, v78
	v_mul_f32_e32 v78, v67, v67
	v_fmaak_f32 v72, v254, v72, 0xc0135761
	v_fmaak_f32 v75, v254, v75, 0xc0135761
	v_fmaak_f32 v76, v254, v76, 0xc0135761
	v_mul_f32_e32 v77, v66, v77
	v_fmaak_f32 v78, v254, v78, 0xc0135761
	v_mul_f32_e32 v72, v68, v72
	v_mul_f32_e32 v75, v65, v75
	v_mul_f32_e32 v76, v70, v76
	v_mul_f32_e32 v78, v67, v78
	v_exp_f32_e32 v77, v77
	v_exp_f32_e32 v72, v72
	v_exp_f32_e32 v75, v75
	v_exp_f32_e32 v76, v76
	v_exp_f32_e32 v82, v78
	v_add_f32_e32 v77, 1.0, v77
	v_add_f32_e32 v72, 1.0, v72
	v_add_f32_e32 v75, 1.0, v75
	v_add_f32_e32 v76, 1.0, v76
	v_rcp_f32_e32 v78, v77
	v_add_f32_e32 v77, 1.0, v79
	v_add_f32_e32 v79, 1.0, v82
	v_rcp_f32_e32 v72, v72
	v_rcp_f32_e32 v73, v73
	v_rcp_f32_e32 v76, v76
	v_rcp_f32_e32 v77, v77
	v_rcp_f32_e32 v79, v79
	v_rcp_f32_e32 v75, v75
	v_pk_mul_f32 v[68:69], v[68:69], v[72:73]
	v_pk_mul_f32 v[70:71], v[70:71], v[76:77]
	v_pk_mul_f32 v[66:67], v[66:67], v[78:79]
	v_pk_mul_f32 v[64:65], v[64:65], v[74:75]
.LBB0_236:
	s_and_b64 vcc, exec, s[6:7]
	v_cvt_pk_bf16_f32 v68, v68, v69
	v_cvt_pk_bf16_f32 v69, v70, v71
	v_cvt_pk_bf16_f32 v70, v64, v65
	v_cvt_pk_bf16_f32 v71, v66, v67
	global_store_dwordx4 v[80:81], v[68:71], off offset:256
	s_cbranch_vccnz .LBB0_238
	v_mul_f32_e32 v65, v56, v56
	v_fmaak_f32 v65, v254, v65, 0xc0135761
	v_mul_f32_e32 v66, v61, v61
	v_mul_f32_e32 v65, v56, v65
	v_fmaak_f32 v66, v254, v66, 0xc0135761
	v_mul_f32_e32 v66, v61, v66
	v_exp_f32_e32 v65, v65
	v_exp_f32_e32 v67, v66
	v_mul_f32_e32 v70, v63, v63
	v_fmaak_f32 v70, v254, v70, 0xc0135761
	v_mul_f32_e32 v70, v63, v70
	v_add_f32_e32 v65, 1.0, v65
	v_mul_f32_e32 v69, v58, v58
	v_mul_f32_e32 v64, v60, v60
	v_rcp_f32_e32 v66, v65
	v_add_f32_e32 v65, 1.0, v67
	v_mul_f32_e32 v67, v57, v57
	v_mul_f32_e32 v68, v62, v62
	v_fmaak_f32 v69, v254, v69, 0xc0135761
	v_exp_f32_e32 v71, v70
	v_mul_f32_e32 v70, v59, v59
	v_fmaak_f32 v64, v254, v64, 0xc0135761
	v_fmaak_f32 v67, v254, v67, 0xc0135761
	v_fmaak_f32 v68, v254, v68, 0xc0135761
	v_mul_f32_e32 v69, v58, v69
	v_fmaak_f32 v70, v254, v70, 0xc0135761
	v_mul_f32_e32 v64, v60, v64
	v_mul_f32_e32 v67, v57, v67
	v_mul_f32_e32 v68, v62, v68
	v_mul_f32_e32 v70, v59, v70
	v_exp_f32_e32 v69, v69
	v_exp_f32_e32 v64, v64
	v_exp_f32_e32 v67, v67
	v_exp_f32_e32 v68, v68
	v_exp_f32_e32 v72, v70
	v_add_f32_e32 v69, 1.0, v69
	v_add_f32_e32 v64, 1.0, v64
	v_add_f32_e32 v67, 1.0, v67
	v_add_f32_e32 v68, 1.0, v68
	v_rcp_f32_e32 v70, v69
	v_add_f32_e32 v69, 1.0, v71
	v_add_f32_e32 v71, 1.0, v72
	v_rcp_f32_e32 v64, v64
	v_rcp_f32_e32 v65, v65
	v_rcp_f32_e32 v68, v68
	v_rcp_f32_e32 v69, v69
	v_rcp_f32_e32 v71, v71
	v_rcp_f32_e32 v67, v67
	v_pk_mul_f32 v[60:61], v[60:61], v[64:65]
	v_pk_mul_f32 v[62:63], v[62:63], v[68:69]
	v_pk_mul_f32 v[58:59], v[58:59], v[70:71]
	v_pk_mul_f32 v[56:57], v[56:57], v[66:67]
.LBB0_238:
	v_lshlrev_b64 v[64:65], 11, v[146:147]
	v_lshl_add_u64 v[64:65], v[148:149], 0, v[64:65]
	v_cvt_pk_bf16_f32 v60, v60, v61
	v_cvt_pk_bf16_f32 v61, v62, v63
	v_cvt_pk_bf16_f32 v62, v56, v57
	v_add_co_u32_e32 v56, vcc, 0x40000, v64
	v_cvt_pk_bf16_f32 v63, v58, v59
	s_nop 1
	v_addc_co_u32_e32 v57, vcc, 0, v65, vcc
	s_and_b64 vcc, exec, s[6:7]
	global_store_dwordx4 v[56:57], v[60:63], off
	s_cbranch_vccnz .LBB0_240
	v_mul_f32_e32 v57, v48, v48
	v_fmaak_f32 v57, v254, v57, 0xc0135761
	v_mul_f32_e32 v58, v53, v53
	v_mul_f32_e32 v57, v48, v57
	v_fmaak_f32 v58, v254, v58, 0xc0135761
	v_mul_f32_e32 v58, v53, v58
	v_exp_f32_e32 v57, v57
	v_exp_f32_e32 v59, v58
	v_mul_f32_e32 v62, v55, v55
	v_fmaak_f32 v62, v254, v62, 0xc0135761
	v_mul_f32_e32 v62, v55, v62
	v_add_f32_e32 v57, 1.0, v57
	v_mul_f32_e32 v61, v50, v50
	v_mul_f32_e32 v56, v52, v52
	v_rcp_f32_e32 v58, v57
	v_add_f32_e32 v57, 1.0, v59
	v_mul_f32_e32 v59, v49, v49
	v_mul_f32_e32 v60, v54, v54
	v_fmaak_f32 v61, v254, v61, 0xc0135761
	v_exp_f32_e32 v63, v62
	v_mul_f32_e32 v62, v51, v51
	v_fmaak_f32 v56, v254, v56, 0xc0135761
	v_fmaak_f32 v59, v254, v59, 0xc0135761
	v_fmaak_f32 v60, v254, v60, 0xc0135761
	v_mul_f32_e32 v61, v50, v61
	v_fmaak_f32 v62, v254, v62, 0xc0135761
	v_mul_f32_e32 v56, v52, v56
	v_mul_f32_e32 v59, v49, v59
	v_mul_f32_e32 v60, v54, v60
	v_mul_f32_e32 v62, v51, v62
	v_exp_f32_e32 v61, v61
	v_exp_f32_e32 v56, v56
	v_exp_f32_e32 v59, v59
	v_exp_f32_e32 v60, v60
	v_exp_f32_e32 v66, v62
	v_add_f32_e32 v61, 1.0, v61
	v_add_f32_e32 v56, 1.0, v56
	v_add_f32_e32 v59, 1.0, v59
	v_add_f32_e32 v60, 1.0, v60
	v_rcp_f32_e32 v62, v61
	v_add_f32_e32 v61, 1.0, v63
	v_add_f32_e32 v63, 1.0, v66
	v_rcp_f32_e32 v56, v56
	v_rcp_f32_e32 v57, v57
	v_rcp_f32_e32 v60, v60
	v_rcp_f32_e32 v61, v61
	v_rcp_f32_e32 v63, v63
	v_rcp_f32_e32 v59, v59
	v_pk_mul_f32 v[52:53], v[52:53], v[56:57]
	v_pk_mul_f32 v[54:55], v[54:55], v[60:61]
	v_pk_mul_f32 v[50:51], v[50:51], v[62:63]
	v_pk_mul_f32 v[48:49], v[48:49], v[58:59]
.LBB0_240:
	v_lshl_add_u64 v[56:57], v[64:65], 0, s[8:9]
	s_and_b64 vcc, exec, s[6:7]
	v_cvt_pk_bf16_f32 v52, v52, v53
	v_cvt_pk_bf16_f32 v53, v54, v55
	v_cvt_pk_bf16_f32 v54, v48, v49
	v_cvt_pk_bf16_f32 v55, v50, v51
	global_store_dwordx4 v[56:57], v[52:55], off offset:256
	s_cbranch_vccnz .LBB0_242
	v_mul_f32_e32 v49, v40, v40
	v_fmaak_f32 v49, v254, v49, 0xc0135761
	v_mul_f32_e32 v50, v45, v45
	v_mul_f32_e32 v49, v40, v49
	v_fmaak_f32 v50, v254, v50, 0xc0135761
	v_mul_f32_e32 v50, v45, v50
	v_exp_f32_e32 v49, v49
	v_exp_f32_e32 v51, v50
	v_mul_f32_e32 v54, v47, v47
	v_fmaak_f32 v54, v254, v54, 0xc0135761
	v_mul_f32_e32 v54, v47, v54
	v_add_f32_e32 v49, 1.0, v49
	v_mul_f32_e32 v53, v42, v42
	v_mul_f32_e32 v48, v44, v44
	v_rcp_f32_e32 v50, v49
	v_add_f32_e32 v49, 1.0, v51
	v_mul_f32_e32 v51, v41, v41
	v_mul_f32_e32 v52, v46, v46
	v_fmaak_f32 v53, v254, v53, 0xc0135761
	v_exp_f32_e32 v55, v54
	v_mul_f32_e32 v54, v43, v43
	v_fmaak_f32 v48, v254, v48, 0xc0135761
	v_fmaak_f32 v51, v254, v51, 0xc0135761
	v_fmaak_f32 v52, v254, v52, 0xc0135761
	v_mul_f32_e32 v53, v42, v53
	v_fmaak_f32 v54, v254, v54, 0xc0135761
	v_mul_f32_e32 v48, v44, v48
	v_mul_f32_e32 v51, v41, v51
	v_mul_f32_e32 v52, v46, v52
	v_mul_f32_e32 v54, v43, v54
	v_exp_f32_e32 v53, v53
	v_exp_f32_e32 v48, v48
	v_exp_f32_e32 v51, v51
	v_exp_f32_e32 v52, v52
	v_exp_f32_e32 v56, v54
	v_add_f32_e32 v53, 1.0, v53
	v_add_f32_e32 v48, 1.0, v48
	v_add_f32_e32 v51, 1.0, v51
	v_add_f32_e32 v52, 1.0, v52
	v_rcp_f32_e32 v54, v53
	v_add_f32_e32 v53, 1.0, v55
	v_add_f32_e32 v55, 1.0, v56
	v_rcp_f32_e32 v48, v48
	v_rcp_f32_e32 v49, v49
	v_rcp_f32_e32 v52, v52
	v_rcp_f32_e32 v53, v53
	v_rcp_f32_e32 v55, v55
	v_rcp_f32_e32 v51, v51
	v_pk_mul_f32 v[44:45], v[44:45], v[48:49]
	v_pk_mul_f32 v[46:47], v[46:47], v[52:53]
	v_pk_mul_f32 v[42:43], v[42:43], v[54:55]
	v_pk_mul_f32 v[40:41], v[40:41], v[50:51]
.LBB0_242:
	v_lshlrev_b64 v[48:49], 11, v[146:147]
	v_lshl_add_u64 v[48:49], v[148:149], 0, v[48:49]
	v_cvt_pk_bf16_f32 v44, v44, v45
	v_cvt_pk_bf16_f32 v45, v46, v47
	v_cvt_pk_bf16_f32 v46, v40, v41
	v_add_co_u32_e32 v40, vcc, 0x48000, v48
	v_cvt_pk_bf16_f32 v47, v42, v43
	s_nop 1
	v_addc_co_u32_e32 v41, vcc, 0, v49, vcc
	s_and_b64 vcc, exec, s[6:7]
	global_store_dwordx4 v[40:41], v[44:47], off
	s_cbranch_vccnz .LBB0_244
	v_mul_f32_e32 v41, v32, v32
	v_fmaak_f32 v41, v254, v41, 0xc0135761
	v_mul_f32_e32 v42, v37, v37
	v_mul_f32_e32 v41, v32, v41
	v_fmaak_f32 v42, v254, v42, 0xc0135761
	v_mul_f32_e32 v42, v37, v42
	v_exp_f32_e32 v41, v41
	v_exp_f32_e32 v43, v42
	v_mul_f32_e32 v46, v39, v39
	v_fmaak_f32 v46, v254, v46, 0xc0135761
	v_mul_f32_e32 v46, v39, v46
	v_add_f32_e32 v41, 1.0, v41
	v_mul_f32_e32 v45, v34, v34
	v_mul_f32_e32 v40, v36, v36
	v_rcp_f32_e32 v42, v41
	v_add_f32_e32 v41, 1.0, v43
	v_mul_f32_e32 v43, v33, v33
	v_mul_f32_e32 v44, v38, v38
	v_fmaak_f32 v45, v254, v45, 0xc0135761
	v_exp_f32_e32 v47, v46
	v_mul_f32_e32 v46, v35, v35
	v_fmaak_f32 v40, v254, v40, 0xc0135761
	v_fmaak_f32 v43, v254, v43, 0xc0135761
	v_fmaak_f32 v44, v254, v44, 0xc0135761
	v_mul_f32_e32 v45, v34, v45
	v_fmaak_f32 v46, v254, v46, 0xc0135761
	v_mul_f32_e32 v40, v36, v40
	v_mul_f32_e32 v43, v33, v43
	v_mul_f32_e32 v44, v38, v44
	v_mul_f32_e32 v46, v35, v46
	v_exp_f32_e32 v45, v45
	v_exp_f32_e32 v40, v40
	v_exp_f32_e32 v43, v43
	v_exp_f32_e32 v44, v44
	v_exp_f32_e32 v50, v46
	v_add_f32_e32 v45, 1.0, v45
	v_add_f32_e32 v40, 1.0, v40
	v_add_f32_e32 v43, 1.0, v43
	v_add_f32_e32 v44, 1.0, v44
	v_rcp_f32_e32 v46, v45
	v_add_f32_e32 v45, 1.0, v47
	v_add_f32_e32 v47, 1.0, v50
	v_rcp_f32_e32 v40, v40
	v_rcp_f32_e32 v41, v41
	v_rcp_f32_e32 v44, v44
	v_rcp_f32_e32 v45, v45
	v_rcp_f32_e32 v47, v47
	v_rcp_f32_e32 v43, v43
	v_pk_mul_f32 v[36:37], v[36:37], v[40:41]
	v_pk_mul_f32 v[38:39], v[38:39], v[44:45]
	v_pk_mul_f32 v[34:35], v[34:35], v[46:47]
	v_pk_mul_f32 v[32:33], v[32:33], v[42:43]
.LBB0_244:
	v_lshl_add_u64 v[40:41], v[48:49], 0, s[16:17]
	s_and_b64 vcc, exec, s[6:7]
	v_cvt_pk_bf16_f32 v36, v36, v37
	v_cvt_pk_bf16_f32 v37, v38, v39
	v_cvt_pk_bf16_f32 v38, v32, v33
	v_cvt_pk_bf16_f32 v39, v34, v35
	global_store_dwordx4 v[40:41], v[36:39], off offset:256
	s_cbranch_vccnz .LBB0_246
	v_mul_f32_e32 v33, v24, v24
	v_fmaak_f32 v33, v254, v33, 0xc0135761
	v_mul_f32_e32 v34, v29, v29
	v_mul_f32_e32 v33, v24, v33
	v_fmaak_f32 v34, v254, v34, 0xc0135761
	v_mul_f32_e32 v34, v29, v34
	v_exp_f32_e32 v33, v33
	v_exp_f32_e32 v35, v34
	v_mul_f32_e32 v38, v31, v31
	v_fmaak_f32 v38, v254, v38, 0xc0135761
	v_mul_f32_e32 v38, v31, v38
	v_add_f32_e32 v33, 1.0, v33
	v_mul_f32_e32 v37, v26, v26
	v_mul_f32_e32 v32, v28, v28
	v_rcp_f32_e32 v34, v33
	v_add_f32_e32 v33, 1.0, v35
	v_mul_f32_e32 v35, v25, v25
	v_mul_f32_e32 v36, v30, v30
	v_fmaak_f32 v37, v254, v37, 0xc0135761
	v_exp_f32_e32 v39, v38
	v_mul_f32_e32 v38, v27, v27
	v_fmaak_f32 v32, v254, v32, 0xc0135761
	v_fmaak_f32 v35, v254, v35, 0xc0135761
	v_fmaak_f32 v36, v254, v36, 0xc0135761
	v_mul_f32_e32 v37, v26, v37
	v_fmaak_f32 v38, v254, v38, 0xc0135761
	v_mul_f32_e32 v32, v28, v32
	v_mul_f32_e32 v35, v25, v35
	v_mul_f32_e32 v36, v30, v36
	v_mul_f32_e32 v38, v27, v38
	v_exp_f32_e32 v37, v37
	v_exp_f32_e32 v32, v32
	v_exp_f32_e32 v35, v35
	v_exp_f32_e32 v36, v36
	v_exp_f32_e32 v40, v38
	v_add_f32_e32 v37, 1.0, v37
	v_add_f32_e32 v32, 1.0, v32
	v_add_f32_e32 v35, 1.0, v35
	v_add_f32_e32 v36, 1.0, v36
	v_rcp_f32_e32 v38, v37
	v_add_f32_e32 v37, 1.0, v39
	v_add_f32_e32 v39, 1.0, v40
	v_rcp_f32_e32 v32, v32
	v_rcp_f32_e32 v33, v33
	v_rcp_f32_e32 v36, v36
	v_rcp_f32_e32 v37, v37
	v_rcp_f32_e32 v39, v39
	v_rcp_f32_e32 v35, v35
	v_pk_mul_f32 v[28:29], v[28:29], v[32:33]
	v_pk_mul_f32 v[30:31], v[30:31], v[36:37]
	v_pk_mul_f32 v[26:27], v[26:27], v[38:39]
	v_pk_mul_f32 v[24:25], v[24:25], v[34:35]
.LBB0_246:
	v_lshlrev_b64 v[32:33], 11, v[146:147]
	v_lshl_add_u64 v[32:33], v[148:149], 0, v[32:33]
	v_cvt_pk_bf16_f32 v28, v28, v29
	v_cvt_pk_bf16_f32 v29, v30, v31
	v_cvt_pk_bf16_f32 v30, v24, v25
	v_add_co_u32_e32 v24, vcc, 0x50000, v32
	v_cvt_pk_bf16_f32 v31, v26, v27
	s_nop 1
	v_addc_co_u32_e32 v25, vcc, 0, v33, vcc
	s_and_b64 vcc, exec, s[6:7]
	global_store_dwordx4 v[24:25], v[28:31], off
	s_cbranch_vccnz .LBB0_248
	v_mul_f32_e32 v25, v16, v16
	v_fmaak_f32 v25, v254, v25, 0xc0135761
	v_mul_f32_e32 v26, v21, v21
	v_mul_f32_e32 v25, v16, v25
	v_fmaak_f32 v26, v254, v26, 0xc0135761
	v_mul_f32_e32 v26, v21, v26
	v_exp_f32_e32 v25, v25
	v_exp_f32_e32 v27, v26
	v_mul_f32_e32 v30, v23, v23
	v_fmaak_f32 v30, v254, v30, 0xc0135761
	v_mul_f32_e32 v30, v23, v30
	v_add_f32_e32 v25, 1.0, v25
	v_mul_f32_e32 v29, v18, v18
	v_mul_f32_e32 v24, v20, v20
	v_rcp_f32_e32 v26, v25
	v_add_f32_e32 v25, 1.0, v27
	v_mul_f32_e32 v27, v17, v17
	v_mul_f32_e32 v28, v22, v22
	v_fmaak_f32 v29, v254, v29, 0xc0135761
	v_exp_f32_e32 v31, v30
	v_mul_f32_e32 v30, v19, v19
	v_fmaak_f32 v24, v254, v24, 0xc0135761
	v_fmaak_f32 v27, v254, v27, 0xc0135761
	v_fmaak_f32 v28, v254, v28, 0xc0135761
	v_mul_f32_e32 v29, v18, v29
	v_fmaak_f32 v30, v254, v30, 0xc0135761
	v_mul_f32_e32 v24, v20, v24
	v_mul_f32_e32 v27, v17, v27
	v_mul_f32_e32 v28, v22, v28
	v_mul_f32_e32 v30, v19, v30
	v_exp_f32_e32 v29, v29
	v_exp_f32_e32 v24, v24
	v_exp_f32_e32 v27, v27
	v_exp_f32_e32 v28, v28
	v_exp_f32_e32 v34, v30
	v_add_f32_e32 v29, 1.0, v29
	v_add_f32_e32 v24, 1.0, v24
	v_add_f32_e32 v27, 1.0, v27
	v_add_f32_e32 v28, 1.0, v28
	v_rcp_f32_e32 v30, v29
	v_add_f32_e32 v29, 1.0, v31
	v_add_f32_e32 v31, 1.0, v34
	v_rcp_f32_e32 v24, v24
	v_rcp_f32_e32 v25, v25
	v_rcp_f32_e32 v28, v28
	v_rcp_f32_e32 v29, v29
	v_rcp_f32_e32 v31, v31
	v_rcp_f32_e32 v27, v27
	v_pk_mul_f32 v[20:21], v[20:21], v[24:25]
	v_pk_mul_f32 v[22:23], v[22:23], v[28:29]
	v_pk_mul_f32 v[18:19], v[18:19], v[30:31]
	v_pk_mul_f32 v[16:17], v[16:17], v[26:27]
.LBB0_248:
	v_lshl_add_u64 v[24:25], v[32:33], 0, s[18:19]
	s_and_b64 vcc, exec, s[6:7]
	v_cvt_pk_bf16_f32 v20, v20, v21
	v_cvt_pk_bf16_f32 v21, v22, v23
	v_cvt_pk_bf16_f32 v22, v16, v17
	v_cvt_pk_bf16_f32 v23, v18, v19
	global_store_dwordx4 v[24:25], v[20:23], off offset:256
	s_cbranch_vccnz .LBB0_250
	v_mul_f32_e32 v17, v8, v8
	v_fmaak_f32 v17, v254, v17, 0xc0135761
	v_mul_f32_e32 v18, v13, v13
	v_mul_f32_e32 v17, v8, v17
	v_fmaak_f32 v18, v254, v18, 0xc0135761
	v_mul_f32_e32 v18, v13, v18
	v_exp_f32_e32 v17, v17
	v_exp_f32_e32 v19, v18
	v_mul_f32_e32 v22, v15, v15
	v_fmaak_f32 v22, v254, v22, 0xc0135761
	v_mul_f32_e32 v22, v15, v22
	v_add_f32_e32 v17, 1.0, v17
	v_mul_f32_e32 v21, v10, v10
	v_mul_f32_e32 v16, v12, v12
	v_rcp_f32_e32 v18, v17
	v_add_f32_e32 v17, 1.0, v19
	v_mul_f32_e32 v19, v9, v9
	v_mul_f32_e32 v20, v14, v14
	v_fmaak_f32 v21, v254, v21, 0xc0135761
	v_exp_f32_e32 v23, v22
	v_mul_f32_e32 v22, v11, v11
	v_fmaak_f32 v16, v254, v16, 0xc0135761
	v_fmaak_f32 v19, v254, v19, 0xc0135761
	v_fmaak_f32 v20, v254, v20, 0xc0135761
	v_mul_f32_e32 v21, v10, v21
	v_fmaak_f32 v22, v254, v22, 0xc0135761
	v_mul_f32_e32 v16, v12, v16
	v_mul_f32_e32 v19, v9, v19
	v_mul_f32_e32 v20, v14, v20
	v_mul_f32_e32 v22, v11, v22
	v_exp_f32_e32 v21, v21
	v_exp_f32_e32 v16, v16
	v_exp_f32_e32 v19, v19
	v_exp_f32_e32 v20, v20
	v_exp_f32_e32 v24, v22
	v_add_f32_e32 v21, 1.0, v21
	v_add_f32_e32 v16, 1.0, v16
	v_add_f32_e32 v19, 1.0, v19
	v_add_f32_e32 v20, 1.0, v20
	v_rcp_f32_e32 v22, v21
	v_add_f32_e32 v21, 1.0, v23
	v_add_f32_e32 v23, 1.0, v24
	v_rcp_f32_e32 v16, v16
	v_rcp_f32_e32 v17, v17
	v_rcp_f32_e32 v20, v20
	v_rcp_f32_e32 v21, v21
	v_rcp_f32_e32 v23, v23
	v_rcp_f32_e32 v19, v19
	v_pk_mul_f32 v[12:13], v[12:13], v[16:17]
	v_pk_mul_f32 v[14:15], v[14:15], v[20:21]
	v_pk_mul_f32 v[10:11], v[10:11], v[22:23]
	v_pk_mul_f32 v[8:9], v[8:9], v[18:19]
.LBB0_250:
	v_lshlrev_b64 v[16:17], 11, v[146:147]
	v_lshl_add_u64 v[16:17], v[148:149], 0, v[16:17]
	v_cvt_pk_bf16_f32 v12, v12, v13
	v_cvt_pk_bf16_f32 v13, v14, v15
	v_cvt_pk_bf16_f32 v14, v8, v9
	v_add_co_u32_e32 v8, vcc, 0x58000, v16
	v_cvt_pk_bf16_f32 v15, v10, v11
	s_nop 1
	v_addc_co_u32_e32 v9, vcc, 0, v17, vcc
	s_and_b64 vcc, exec, s[6:7]
	global_store_dwordx4 v[8:9], v[12:15], off
	s_cbranch_vccnz .LBB0_252
	v_mul_f32_e32 v9, v0, v0
	v_fmaak_f32 v9, v254, v9, 0xc0135761
	v_mul_f32_e32 v10, v5, v5
	v_mul_f32_e32 v9, v0, v9
	v_fmaak_f32 v10, v254, v10, 0xc0135761
	v_mul_f32_e32 v10, v5, v10
	v_exp_f32_e32 v9, v9
	v_exp_f32_e32 v11, v10
	v_mul_f32_e32 v14, v7, v7
	v_fmaak_f32 v14, v254, v14, 0xc0135761
	v_mul_f32_e32 v14, v7, v14
	v_add_f32_e32 v9, 1.0, v9
	v_mul_f32_e32 v13, v2, v2
	v_mul_f32_e32 v8, v4, v4
	v_rcp_f32_e32 v10, v9
	v_add_f32_e32 v9, 1.0, v11
	v_mul_f32_e32 v11, v1, v1
	v_mul_f32_e32 v12, v6, v6
	v_fmaak_f32 v13, v254, v13, 0xc0135761
	v_exp_f32_e32 v15, v14
	v_mul_f32_e32 v14, v3, v3
	v_fmaak_f32 v8, v254, v8, 0xc0135761
	v_fmaak_f32 v11, v254, v11, 0xc0135761
	v_fmaak_f32 v12, v254, v12, 0xc0135761
	v_mul_f32_e32 v13, v2, v13
	v_fmaak_f32 v14, v254, v14, 0xc0135761
	v_mul_f32_e32 v8, v4, v8
	v_mul_f32_e32 v11, v1, v11
	v_mul_f32_e32 v12, v6, v12
	v_mul_f32_e32 v14, v3, v14
	v_exp_f32_e32 v13, v13
	v_exp_f32_e32 v8, v8
	v_exp_f32_e32 v11, v11
	v_exp_f32_e32 v12, v12
	v_exp_f32_e32 v18, v14
	v_add_f32_e32 v13, 1.0, v13
	v_add_f32_e32 v8, 1.0, v8
	v_add_f32_e32 v11, 1.0, v11
	v_add_f32_e32 v12, 1.0, v12
	v_rcp_f32_e32 v14, v13
	v_add_f32_e32 v13, 1.0, v15
	v_add_f32_e32 v15, 1.0, v18
	v_rcp_f32_e32 v8, v8
	v_rcp_f32_e32 v9, v9
	v_rcp_f32_e32 v12, v12
	v_rcp_f32_e32 v13, v13
	v_rcp_f32_e32 v15, v15
	v_rcp_f32_e32 v11, v11
	v_pk_mul_f32 v[4:5], v[4:5], v[8:9]
	v_pk_mul_f32 v[6:7], v[6:7], v[12:13]
	v_pk_mul_f32 v[2:3], v[2:3], v[14:15]
	v_pk_mul_f32 v[0:1], v[0:1], v[10:11]
